# v55 + MLA loop: rope-K DMA before the V DMAs, tile barriers wait vmcnt(2) (V tile may stay in flight one more tile); loop exit drains + barrier
# baseline (speedup 1.0000x reference)
.Lmla_nopf_stub:
	s_waitcnt vmcnt(0)
	s_branch .Lattn_mla_nopf
.LBB0_543:
	s_mov_b32 s23, s17
	s_mov_b32 s17, s0
	s_add_u32 s4, s38, s20
	s_addc_u32 s5, s39, s21
	s_add_u32 s24, s4, 0x149ec400
	s_addc_u32 s25, s5, 0
	s_mov_b32 m0, s90
	v_lshl_add_u64 v[254:255], v[246:247], 0, s[24:25]
	s_lshl_b32 s18, s22, 14
	global_load_lds_dwordx4 v[254:255], off
	s_add_u32 s24, s4, 0x14a0c400
	s_addc_u32 s25, s5, 0
	s_mov_b32 m0, s91
	v_lshl_add_u64 v[254:255], v[246:247], 0, s[24:25]
	s_add_i32 s1, s89, s18
	global_load_lds_dwordx4 v[254:255], off
	s_add_u32 s24, s38, s88
	s_addc_u32 s25, s39, s87
	s_add_u32 s24, s24, s36
	s_addc_u32 s25, s25, s37
	s_mov_b32 m0, s92
	v_lshl_add_u64 v[254:255], v[250:251], 0, s[24:25]
	global_load_lds_dwordx4 v[254:255], off
	s_add_u32 s24, s4, 0x149ec500
	s_addc_u32 s25, s5, 0
	s_mov_b32 m0, s1
	v_lshl_add_u64 v[254:255], v[248:249], 0, s[24:25]
	global_load_lds_dwordx4 v[254:255], off
	s_add_u32 s24, s4, 0x14a0c500
	s_addc_u32 s25, s5, 0
	s_add_i32 m0, s1, 0x2000
	v_lshl_add_u64 v[254:255], v[248:249], 0, s[24:25]
	global_load_lds_dwordx4 v[254:255], off
	s_add_i32 s71, 0, 0x10000
	ds_read_b128 v[66:69], v174 offset:49152
	ds_read_b128 v[70:73], v174 offset:57344
	ds_read_b128 v[206:209], v176 offset:49152
	ds_read_b128 v[210:213], v176 offset:57344
	v_fma_f32 v152, v74, s34, v146
	v_fma_f32 v153, v75, s34, v146
	v_fma_f32 v150, v76, s34, v146
	v_fma_f32 v151, v77, s34, v146
	v_fma_f32 v148, v78, s34, v146
	v_fma_f32 v149, v79, s34, v146
	v_fma_f32 v147, v81, s34, v146
	v_fma_f32 v146, v80, s34, v146
	v_exp_f32_e32 v229, v229
	v_exp_f32_e32 v231, v231
	v_exp_f32_e32 v227, v227
	v_exp_f32_e32 v230, v230
	v_exp_f32_e32 v226, v226
	v_exp_f32_e32 v228, v228
	s_waitcnt lgkmcnt(0)
	v_mfma_f32_32x32x16_bf16 v[82:97], v[66:69], v[142:145], 0
	s_add_i32 s0, 0, 0x16000
	v_exp_f32_e32 v240, v146
	v_add_f32_e32 v146, 0, v229
	v_add_f32_e32 v146, v231, v146
	v_add_f32_e32 v146, v227, v146
	v_add_f32_e32 v146, v230, v146
	v_add_f32_e32 v146, v226, v146
	v_exp_f32_e32 v224, v224
	v_exp_f32_e32 v225, v225
	v_exp_f32_e32 v221, v221
	v_exp_f32_e32 v223, v223
	v_mfma_f32_32x32x16_bf16 v[66:81], v[70:73], v[142:145], 0
	v_exp_f32_e32 v220, v220
	v_exp_f32_e32 v222, v222
	v_add_f32_e32 v146, v228, v146
	v_add_f32_e32 v146, v224, v146
	v_add_f32_e32 v146, v225, v146
	v_add_f32_e32 v146, v221, v146
	v_add_f32_e32 v146, v223, v146
	v_add_f32_e32 v146, v220, v146
	v_add_f32_e32 v146, v222, v146
	v_exp_f32_e32 v217, v217
	v_exp_f32_e32 v219, v219
	v_exp_f32_e32 v216, v216
	v_exp_f32_e32 v218, v218
	v_mfma_f32_32x32x16_bf16 v[82:97], v[206:209], v[138:141], v[82:97]
	v_exp_f32_e32 v164, v164
	v_add_f32_e32 v146, v217, v146
	v_exp_f32_e32 v165, v165
	v_add_f32_e32 v146, v219, v146
	v_exp_f32_e32 v197, v162
	v_add_f32_e32 v146, v216, v146
	v_add_f32_e32 v146, v218, v146
	v_mfma_f32_32x32x16_bf16 v[66:81], v[210:213], v[138:141], v[66:81]
	ds_read_b128 v[206:209], v178 offset:49152
	ds_read_b128 v[210:213], v178 offset:57344
	v_exp_f32_e32 v156, v156
	v_add_f32_e32 v146, v164, v146
	v_exp_f32_e32 v157, v157
	v_add_f32_e32 v146, v165, v146
	v_add_f32_e32 v146, v197, v146
	v_exp_f32_e32 v241, v147
	s_waitcnt lgkmcnt(0)
	v_mfma_f32_32x32x16_bf16 v[82:97], v[206:209], v[134:137], v[82:97]
	v_mfma_f32_32x32x16_bf16 v[66:81], v[210:213], v[134:137], v[66:81]
	ds_read_b128 v[208:211], v180 offset:49152
	ds_read_b128 v[212:215], v180 offset:57344
	s_waitcnt lgkmcnt(0)
	v_mfma_f32_32x32x16_bf16 v[82:97], v[208:211], v[130:133], v[82:97]
	v_mfma_f32_32x32x16_bf16 v[66:81], v[212:215], v[130:133], v[66:81]
	ds_read_b128 v[208:211], v182 offset:49152
	ds_read_b128 v[212:215], v182 offset:57344
	s_waitcnt lgkmcnt(0)
	v_mfma_f32_32x32x16_bf16 v[82:97], v[208:211], v[126:129], v[82:97]
	v_mfma_f32_32x32x16_bf16 v[66:81], v[212:215], v[126:129], v[66:81]
	ds_read_b128 v[210:213], v186 offset:49152
	ds_read_b128 v[232:235], v186 offset:57344
	s_waitcnt lgkmcnt(0)
	v_mfma_f32_32x32x16_bf16 v[82:97], v[210:213], v[122:125], v[82:97]
	v_mfma_f32_32x32x16_bf16 v[66:81], v[232:235], v[122:125], v[66:81]
	ds_read_b128 v[210:213], v188 offset:49152
	ds_read_b128 v[232:235], v188 offset:57344
	s_waitcnt lgkmcnt(0)
	v_mfma_f32_32x32x16_bf16 v[82:97], v[210:213], v[118:121], v[82:97]
	v_mfma_f32_32x32x16_bf16 v[66:81], v[232:235], v[118:121], v[66:81]
	ds_read_b128 v[212:215], v190 offset:49152
	ds_read_b128 v[232:235], v190 offset:57344
	s_waitcnt lgkmcnt(0)
	v_mfma_f32_32x32x16_bf16 v[82:97], v[212:215], v[114:117], v[82:97]
	v_mfma_f32_32x32x16_bf16 v[66:81], v[232:235], v[114:117], v[66:81]
	ds_read_b128 v[212:215], v192 offset:8192
	ds_read_b128 v[232:235], v192 offset:12288
	s_waitcnt lgkmcnt(0)
	v_mfma_f32_32x32x16_bf16 v[82:97], v[212:215], v[110:113], v[82:97]
	v_exp_f32_e32 v215, v163
	s_nop 0
	v_add_f32_e32 v146, v215, v146
	v_mfma_f32_32x32x16_bf16 v[66:81], v[232:235], v[110:113], v[66:81]
	s_lshl_b32 s24, s17, 14
	v_add_u32_e32 v245, s24, v200
	ds_read_b64_tr_b16 v[206:207], v245 offset:0
	ds_read_b64_tr_b16 v[208:209], v245 offset:0x800
	ds_read_b64_tr_b16 v[210:211], v245 offset:0x1000
	ds_read_b64_tr_b16 v[212:213], v245 offset:0x1800
	ds_read_b128 v[232:235], v194 offset:8192
	ds_read_b128 v[236:239], v194 offset:12288
	v_add_f32_e32 v146, v156, v146
	v_add_f32_e32 v146, v157, v146
	s_waitcnt lgkmcnt(0)
	v_mfma_f32_32x32x16_bf16 v[82:97], v[232:235], v[106:109], v[82:97]
	v_mfma_f32_32x32x16_bf16 v[66:81], v[236:239], v[106:109], v[66:81]
	ds_read_b128 v[232:235], v196 offset:8192
	ds_read_b128 v[236:239], v196 offset:12288
	s_waitcnt lgkmcnt(0)
	v_mfma_f32_32x32x16_bf16 v[82:97], v[232:235], v[102:105], v[82:97]
	v_mfma_f32_32x32x16_bf16 v[66:81], v[236:239], v[102:105], v[66:81]
	ds_read_b128 v[232:235], v199 offset:8192
	ds_read_b128 v[236:239], v199 offset:12288
	s_waitcnt lgkmcnt(0)
	v_mfma_f32_32x32x16_bf16 v[82:97], v[232:235], v[98:101], v[82:97]
	v_exp_f32_e32 v232, v154
	v_exp_f32_e32 v233, v155
	v_exp_f32_e32 v234, v152
	v_exp_f32_e32 v235, v153
	v_add_f32_e32 v146, v232, v146
	v_add_f32_e32 v146, v233, v146
	v_add_f32_e32 v146, v234, v146
	v_mfma_f32_32x32x16_bf16 v[66:81], v[236:239], v[98:101], v[66:81]
	v_exp_f32_e32 v236, v150
	v_exp_f32_e32 v237, v151
	v_exp_f32_e32 v238, v148
	v_exp_f32_e32 v239, v149
	v_add_f32_e32 v146, v235, v146
	v_add_f32_e32 v146, v236, v146
	v_add_f32_e32 v146, v237, v146
	v_add_f32_e32 v146, v238, v146
	v_add_f32_e32 v146, v239, v146
	v_add_f32_e32 v146, v240, v146
	v_add_f32_e32 v162, v241, v146
	v_mov_b32_e32 v163, v162
	s_nop 1
	v_permlane32_swap_b32_e32 v162, v163
	v_cvt_pk_bf16_f32 v146, v229, v231
	v_cvt_pk_bf16_f32 v147, v227, v230
	v_cvt_pk_bf16_f32 v148, v226, v228
	v_cvt_pk_bf16_f32 v149, v224, v225
	v_cvt_pk_bf16_f32 v150, v221, v223
	v_cvt_pk_bf16_f32 v151, v220, v222
	v_cvt_pk_bf16_f32 v152, v217, v219
	v_cvt_pk_bf16_f32 v153, v216, v218
	v_cvt_pk_bf16_f32 v154, v164, v165
	v_cvt_pk_bf16_f32 v155, v197, v215
	v_cvt_pk_bf16_f32 v156, v156, v157
	v_cvt_pk_bf16_f32 v157, v232, v233
	v_cvt_pk_bf16_f32 v216, v234, v235
	v_cvt_pk_bf16_f32 v217, v236, v237
	v_cvt_pk_bf16_f32 v218, v238, v239
	v_cvt_pk_bf16_f32 v219, v240, v241
	s_nop 0
	v_permlane32_swap_b32_e32 v146, v148
	v_permlane32_swap_b32_e32 v147, v149
	v_permlane32_swap_b32_e32 v150, v152
	v_permlane32_swap_b32_e32 v151, v153
	v_permlane32_swap_b32_e32 v154, v156
	v_permlane32_swap_b32_e32 v155, v157
	v_permlane32_swap_b32_e32 v216, v218
	v_permlane32_swap_b32_e32 v217, v219
	s_lshl_b32 s24, s17, 14
	v_add_u32_e32 v197, s24, v200
	ds_read_b64_tr_b16 v[228:229], v197 offset:0x2000
	ds_read_b64_tr_b16 v[230:231], v197 offset:0x2800
	ds_read_b64_tr_b16 v[232:233], v197 offset:0x3000
	ds_read_b64_tr_b16 v[234:235], v197 offset:0x3800
	s_nop 0
	v_mfma_f32_32x32x16_bf16 v[2:17], v[146:149], v[206:209], v[2:17]
	ds_read_b64_tr_b16 v[220:221], v197 offset:0x200
	ds_read_b64_tr_b16 v[222:223], v197 offset:0xa00
	v_max_f32_e32 v164, v83, v83
	v_max_f32_e32 v165, v82, v82
	v_max_f32_e32 v164, v165, v164
	v_max3_f32 v164, v164, v84, v85
	v_max3_f32 v164, v164, v86, v87
	v_mfma_f32_32x32x16_bf16 v[2:17], v[150:153], v[210:213], v[2:17]
	ds_read_b64_tr_b16 v[224:225], v197 offset:0x1200
	ds_read_b64_tr_b16 v[226:227], v197 offset:0x1a00
	v_max3_f32 v164, v164, v88, v89
	v_max3_f32 v164, v164, v90, v91
	v_max3_f32 v164, v164, v92, v93
	v_max3_f32 v164, v164, v94, v95
	v_max3_f32 v164, v164, v96, v97
	s_waitcnt lgkmcnt(6)
	v_mfma_f32_32x32x16_bf16 v[2:17], v[154:157], v[228:231], v[2:17]
	ds_read_b64_tr_b16 v[228:229], v197 offset:0x2200
	ds_read_b64_tr_b16 v[230:231], v197 offset:0x2a00
	ds_read_b64_tr_b16 v[236:237], v197 offset:0x3200
	ds_read_b64_tr_b16 v[238:239], v197 offset:0x3a00
	s_waitcnt lgkmcnt(8)
	v_mfma_f32_32x32x16_bf16 v[2:17], v[216:219], v[232:235], v[2:17]
	s_waitcnt lgkmcnt(6)
	v_mfma_f32_32x32x16_bf16 v[50:65], v[146:149], v[220:223], v[50:65]
	v_max3_f32 v164, v164, v66, v67
	v_max3_f32 v164, v164, v68, v69
	v_max3_f32 v164, v164, v70, v71
	v_max3_f32 v164, v164, v72, v73
	v_max3_f32 v164, v164, v74, v75
	v_max3_f32 v164, v164, v76, v77
	v_max3_f32 v164, v164, v78, v79
	s_waitcnt lgkmcnt(4)
	v_mfma_f32_32x32x16_bf16 v[50:65], v[150:153], v[224:227], v[50:65]
	v_max3_f32 v164, v164, v80, v81
	v_mov_b32_e32 v165, v164
	s_nop 1
	v_permlane32_swap_b32_e32 v164, v165
	ds_read_b64_tr_b16 v[220:221], v197 offset:0x400
	v_max_f32_e32 v165, v165, v165
	v_max_f32_e32 v164, v164, v164
	s_waitcnt lgkmcnt(3)
	v_mfma_f32_32x32x16_bf16 v[50:65], v[154:157], v[228:231], v[50:65]
	ds_read_b64_tr_b16 v[222:223], v197 offset:0xc00
	v_max_f32_e32 v164, v164, v165
	v_max_f32_e32 v165, v202, v202
	ds_read_b64_tr_b16 v[224:225], v197 offset:0x1400
	v_max_f32_e32 v165, v165, v164
	ds_read_b64_tr_b16 v[226:227], v197 offset:0x1c00
	v_sub_f32_e32 v215, v164, v202
	s_waitcnt lgkmcnt(4)
	v_mfma_f32_32x32x16_bf16 v[50:65], v[216:219], v[236:239], v[50:65]
	v_sub_f32_e32 v164, v202, v165
	ds_read_b64_tr_b16 v[228:229], v197 offset:0x2400
	v_mul_f32_e32 v164, 0x3dd53b94, v164
	ds_read_b64_tr_b16 v[230:231], v197 offset:0x2c00
	v_exp_f32_e32 v164, v164
	ds_read_b64_tr_b16 v[232:233], v197 offset:0x3400
	v_cmp_ge_f32_e32 vcc, s77, v215
	ds_read_b64_tr_b16 v[234:235], v197 offset:0x3c00
	s_cmp_eq_u64 vcc, exec
	s_cselect_b64 s[4:5], -1, 0
	v_cndmask_b32_e64 v164, v164, 1.0, s[4:5]
	s_waitcnt lgkmcnt(6)
	v_mfma_f32_32x32x16_bf16 v[34:49], v[146:149], v[220:223], v[34:49]
	ds_read_b64_tr_b16 v[220:221], v197 offset:0x600
	ds_read_b64_tr_b16 v[222:223], v197 offset:0xe00
	s_waitcnt lgkmcnt(6)
	v_mfma_f32_32x32x16_bf16 v[34:49], v[150:153], v[224:227], v[34:49]
	ds_read_b64_tr_b16 v[224:225], v197 offset:0x1600
	ds_read_b64_tr_b16 v[226:227], v197 offset:0x1e00
	s_waitcnt lgkmcnt(6)
	v_mfma_f32_32x32x16_bf16 v[34:49], v[154:157], v[228:231], v[34:49]
	ds_read_b64_tr_b16 v[228:229], v197 offset:0x2600
	ds_read_b64_tr_b16 v[230:231], v197 offset:0x2e00
	ds_read_b64_tr_b16 v[236:237], v197 offset:0x3600
	ds_read_b64_tr_b16 v[238:239], v197 offset:0x3e00
	s_waitcnt lgkmcnt(8)
	v_mfma_f32_32x32x16_bf16 v[34:49], v[216:219], v[232:235], v[34:49]
	s_waitcnt lgkmcnt(6)
	v_mfma_f32_32x32x16_bf16 v[18:33], v[146:149], v[220:223], v[18:33]
	v_cmp_gt_f32_e32 vcc, 1.0, v164
	s_waitcnt lgkmcnt(4)
	v_mfma_f32_32x32x16_bf16 v[18:33], v[150:153], v[224:227], v[18:33]
	s_waitcnt lgkmcnt(2)
	v_mfma_f32_32x32x16_bf16 v[18:33], v[154:157], v[228:231], v[18:33]
	s_waitcnt lgkmcnt(0)
	v_mfma_f32_32x32x16_bf16 v[18:33], v[216:219], v[236:239], v[18:33]
	s_cbranch_vccz .LBB0_547
	s_and_saveexec_b64 s[0:1], s[2:3]
	ds_write_b32 v170, v164 offset:128
	s_or_b64 exec, exec, s[0:1]
	s_waitcnt lgkmcnt(0)
	ds_read_b128 v[146:149], v158 offset:224
	ds_read_b128 v[150:153], v158 offset:192
	ds_read_b128 v[154:157], v158 offset:160
	ds_read_b128 v[216:219], v158 offset:128
	s_waitcnt lgkmcnt(0)
	v_pk_mul_f32 v[16:17], v[16:17], v[148:149]
	v_pk_mul_f32 v[12:13], v[12:13], v[152:153]
	v_pk_mul_f32 v[8:9], v[8:9], v[156:157]
	v_pk_mul_f32 v[4:5], v[4:5], v[218:219]
	v_pk_mul_f32 v[14:15], v[14:15], v[146:147]
	v_pk_mul_f32 v[10:11], v[10:11], v[150:151]
	v_pk_mul_f32 v[6:7], v[6:7], v[154:155]
	v_pk_mul_f32 v[2:3], v[2:3], v[216:217]
	v_pk_mul_f32 v[64:65], v[64:65], v[148:149]
	v_pk_mul_f32 v[60:61], v[60:61], v[152:153]
	v_pk_mul_f32 v[56:57], v[56:57], v[156:157]
	v_pk_mul_f32 v[52:53], v[52:53], v[218:219]
	v_pk_mul_f32 v[62:63], v[62:63], v[146:147]
	v_pk_mul_f32 v[58:59], v[58:59], v[150:151]
	v_pk_mul_f32 v[54:55], v[54:55], v[154:155]
	v_pk_mul_f32 v[50:51], v[50:51], v[216:217]
	v_pk_mul_f32 v[48:49], v[48:49], v[148:149]
	v_pk_mul_f32 v[44:45], v[44:45], v[152:153]
	v_pk_mul_f32 v[40:41], v[40:41], v[156:157]
	v_pk_mul_f32 v[36:37], v[36:37], v[218:219]
	v_pk_mul_f32 v[46:47], v[46:47], v[146:147]
	v_pk_mul_f32 v[42:43], v[42:43], v[150:151]
	v_pk_mul_f32 v[38:39], v[38:39], v[154:155]
	v_pk_mul_f32 v[34:35], v[34:35], v[216:217]
	v_pk_mul_f32 v[32:33], v[32:33], v[148:149]
	v_pk_mul_f32 v[28:29], v[28:29], v[152:153]
	v_pk_mul_f32 v[24:25], v[24:25], v[156:157]
	v_pk_mul_f32 v[20:21], v[20:21], v[218:219]
	v_pk_mul_f32 v[30:31], v[30:31], v[146:147]
	v_pk_mul_f32 v[26:27], v[26:27], v[150:151]
	v_pk_mul_f32 v[22:23], v[22:23], v[154:155]
	v_pk_mul_f32 v[18:19], v[18:19], v[216:217]
.LBB0_547:
	s_waitcnt vmcnt(2)
	s_add_i32 s0, s19, 1
	s_cmp_ge_u32 s0, s86
	s_cselect_b32 s98, 1, 0
	s_waitcnt vmcnt(2)
	s_barrier
.LBB0_549:
	s_cmp_lg_u32 s98, 0
	s_cbranch_scc1 .Lmla_nopf_stub
	s_add_u32 s0, s38, s20
	s_addc_u32 s1, s39, s21
	s_add_u32 s100, s0, s42
	s_addc_u32 s101, s1, s43
	s_mov_b32 m0, s93
	v_lshl_add_u64 v[254:255], v[246:247], 0, s[100:101]
	global_load_lds_dwordx4 v[254:255], off
	s_add_u32 s100, s0, s46
	s_addc_u32 s101, s1, s47
	s_mov_b32 m0, s94
	v_lshl_add_u64 v[254:255], v[246:247], 0, s[100:101]
	global_load_lds_dwordx4 v[254:255], off
	s_add_u32 s100, s38, s88
	s_addc_u32 s101, s39, s87
	s_add_u32 s100, s100, s58
	s_addc_u32 s101, s101, s59
	s_mov_b32 m0, s95
	v_lshl_add_u64 v[254:255], v[250:251], 0, s[100:101]
	global_load_lds_dwordx4 v[254:255], off
	s_add_u32 s100, s0, s44
	s_addc_u32 s101, s1, s45
	s_add_i32 s98, s89, s24
	s_mov_b32 m0, s98
	v_lshl_add_u64 v[254:255], v[248:249], 0, s[100:101]
	global_load_lds_dwordx4 v[254:255], off
	s_add_u32 s100, s0, s50
	s_addc_u32 s101, s1, s51
	s_add_i32 m0, s98, 0x2000
	v_lshl_add_u64 v[254:255], v[248:249], 0, s[100:101]
	global_load_lds_dwordx4 v[254:255], off

.LBB0_553:
	v_cndmask_b32_e64 v202, v202, v165, s[4:5]
	v_mul_f32_e32 v146, 0xbdd53b94, v202
	v_fmamk_f32 v229, v82, 0x3dd53b94, v146
	v_fmamk_f32 v231, v83, 0x3dd53b94, v146
	v_fmamk_f32 v227, v84, 0x3dd53b94, v146
	v_fmamk_f32 v230, v85, 0x3dd53b94, v146
	v_fmamk_f32 v226, v86, 0x3dd53b94, v146
	v_fmamk_f32 v228, v87, 0x3dd53b94, v146
	v_fmamk_f32 v224, v88, 0x3dd53b94, v146
	v_fmamk_f32 v225, v89, 0x3dd53b94, v146
	v_fmamk_f32 v221, v90, 0x3dd53b94, v146
	v_fmamk_f32 v223, v91, 0x3dd53b94, v146
	v_fmamk_f32 v220, v92, 0x3dd53b94, v146
	v_fmamk_f32 v222, v93, 0x3dd53b94, v146
	v_fmamk_f32 v217, v94, 0x3dd53b94, v146
	v_fmamk_f32 v219, v95, 0x3dd53b94, v146
	v_fmamk_f32 v216, v96, 0x3dd53b94, v146
	v_fmamk_f32 v218, v97, 0x3dd53b94, v146
	s_add_u32 s88, s88, 0xf0000
	s_addc_u32 s87, s87, 0
	v_add_f32_e32 v82, v162, v163
	s_waitcnt vmcnt(2)
	s_add_u32 s20, s20, 0x80000
	v_fmac_f32_e32 v82, v201, v171
	v_add_f32_e32 v171, v232, v233
	s_addc_u32 s21, s21, 0
	s_add_i32 s19, s19, 2
	v_fmac_f32_e32 v171, v82, v164
	v_fma_f32 v164, v66, s34, v146
	v_fma_f32 v165, v67, s34, v146
	v_fma_f32 v162, v68, s34, v146
	v_fma_f32 v163, v69, s34, v146
	v_fma_f32 v156, v70, s34, v146
	v_fma_f32 v157, v71, s34, v146
	v_fma_f32 v154, v72, s34, v146
	v_fma_f32 v155, v73, s34, v146
	s_cmp_ge_u32 s19, s86
	s_mov_b32 s0, s22
	s_mov_b32 s22, s23
	v_mov_b32_e32 v201, v215
	s_waitcnt vmcnt(2)
	s_barrier
	s_cbranch_scc0 .LBB0_543
	v_fma_f32 v152, v74, s34, v146
	v_fma_f32 v153, v75, s34, v146
	v_fma_f32 v150, v76, s34, v146
	v_fma_f32 v151, v77, s34, v146
	v_fma_f32 v148, v78, s34, v146
	v_fma_f32 v149, v79, s34, v146
	v_fma_f32 v147, v81, s34, v146
	v_fma_f32 v146, v80, s34, v146
	v_exp_f32_e32 v229, v229
	v_exp_f32_e32 v231, v231
	v_exp_f32_e32 v227, v227
	v_exp_f32_e32 v230, v230
	v_exp_f32_e32 v226, v226
	v_exp_f32_e32 v228, v228
	v_exp_f32_e32 v224, v224
	v_exp_f32_e32 v225, v225
	v_exp_f32_e32 v221, v221
	v_exp_f32_e32 v223, v223
	v_exp_f32_e32 v220, v220
	v_exp_f32_e32 v222, v222
	v_exp_f32_e32 v217, v217
	v_exp_f32_e32 v219, v219
	v_exp_f32_e32 v216, v216
	v_exp_f32_e32 v218, v218
	s_waitcnt vmcnt(0)
	s_barrier
